# v22 + post-attention LN early next-row loads with counted waits + radix-select prefix step as DPP scan (no readlane change)
# baseline (speedup 1.0000x reference)
; DI int bperm_i(int srclane, int v) { return __builtin_amdgcn_ds_bpermute(srclane << 2, v); }
; DI void dsa_index_phase(unsigned char* lds, KParamPtr P, int wv) {
;     ...
;       if (big) {
;         const u32x4 hv = *(const u32x4*)(Hc + lane * 4);
;         const int sloc = (int)(hv.x + hv.y + hv.z + hv.w);
;         int incl = sloc;
; #pragma unroll
;         for (int off = 1; off < 64; off <<= 1) { int v = bperm_i(lane + off, incl); if (lane + off < 64) incl += v; }
;         int cum = incl - sloc;
;         bool found = false; int d = 0, nK = 0;
; #pragma unroll
;     ...
;           const int hbq = (int)hv[bq];
;           if (!found && cum < Kr && Kr <= cum + hbq) { found = true; d = lane * 4 + bq; nK = Kr - cum; }
;           cum += hbq;
;         }
.LBB0_890:
	s_or_b64 exec, exec, s[20:21]
	s_and_saveexec_b64 s[24:25], vcc
	s_cbranch_execz .LBB0_876
	v_lshl_add_u32 v0, v106, 2, v0
	ds_read_b128 v[2:5], v0
	s_waitcnt lgkmcnt(0)
	v_add_u32_e32 v0, v2, v3
	v_add3_u32 v0, v0, v4, v5
	v_mov_b32_e32 v6, v0
	s_nop 1
	v_add_u32_dpp v6, v0, v6 row_shr:1 row_mask:0xf bank_mask:0xf bound_ctrl:0
	v_add_u32_dpp v6, v0, v6 row_shr:2 row_mask:0xf bank_mask:0xf bound_ctrl:0
	v_add_u32_dpp v6, v0, v6 row_shr:3 row_mask:0xf bank_mask:0xf bound_ctrl:0
	s_nop 1
	v_add_u32_dpp v6, v6, v6 row_shr:4 row_mask:0xf bank_mask:0xe
	s_nop 1
	v_add_u32_dpp v6, v6, v6 row_shr:8 row_mask:0xf bank_mask:0xc
	s_nop 1
	v_add_u32_dpp v6, v6, v6 row_bcast:15 row_mask:0xa bank_mask:0xf
	s_nop 1
	v_add_u32_dpp v6, v6, v6 row_bcast:31 row_mask:0xc bank_mask:0xf
	s_nop 1
	v_readlane_b32 s28, v6, 63
	s_nop 0
	v_sub_u32_e32 v7, s28, v6
	v_add_u32_e32 v8, v7, v5
	v_cmp_le_i32_e64 s[20:21], v14, v7
	v_cmp_gt_i32_e64 s[22:23], v14, v8
	v_cmp_le_i32_e64 s[18:19], v14, v8
	s_or_b64 s[22:23], s[20:21], s[22:23]
	v_add_u32_e32 v6, v8, v4
	s_and_saveexec_b64 s[28:29], s[22:23]
	s_xor_b64 s[22:23], exec, s[28:29]
	s_cbranch_execz .LBB0_895
	v_add_u32_e32 v6, v8, v4
	v_cmp_le_i32_e64 s[20:21], v14, v6
	s_xor_b64 s[18:19], s[18:19], -1
	s_and_b64 s[28:29], s[18:19], s[20:21]
	s_mov_b64 s[20:21], 0
	v_mov_b32_e32 v0, 0
	v_mov_b32_e32 v5, 0
	s_and_saveexec_b64 s[18:19], s[28:29]
	s_mov_b64 s[20:21], exec
	v_sub_u32_e32 v0, v14, v8
	v_mov_b32_e32 v5, v116
	s_or_b64 exec, exec, s[18:19]

; DI void ln_mod_phase(KParamPtr P, int wv, const float* src, float* xdst, const float* lng, const float* lnb, const float* sh, const float* sc, bool do_ln, bool write_hb) {
;     ...
; #pragma unroll
;     for (int i = 0; i < 4; ++i) { v[i].x = vn[i][0]; v[i].y = vn[i][1]; v[i].z = vn[i][2]; v[i].w = vn[i][3]; }
;     {
;       const int rn = row + 1 < r1 ? row + 1 : row;
; #pragma unroll
;       for (int i = 0; i < 4; ++i) vn[i] = *(const f32x4*)(src + (size_t)rn * DM + lane * 4 + 256 * i);
;     }
;     if (do_ln) {
;       float s = 0.f;
; #pragma unroll
;       for (int i = 0; i < 4; ++i) s += v[i].x + v[i].y + v[i].z + v[i].w;
;       const float mu = wave_sum(s, lane) * (1.f / 1024.f);
;       float q = 0.f;
; #pragma unroll
;       for (int i = 0; i < 4; ++i) { v[i].x -= mu; v[i].y -= mu; v[i].z -= mu; v[i].w -= mu; q += v[i].x * v[i].x + v[i].y * v[i].y + v[i].z * v[i].z + v[i].w * v[i].w; }
;       const float rstd = rsqrtf(wave_sum(q, lane) * (1.f / 1024.f) + 1e-5f);
.LBB0_1255:
	s_or_b64 exec, exec, s[4:5]
	v_add_u32_e32 v196, 1, v86
	v_cmp_lt_i32_e32 vcc, v196, v96
	v_cndmask_b32_e32 v196, v86, v196, vcc
	v_ashrrev_i32_e32 v197, 31, v196
	v_lshlrev_b64 v[196:197], 12, v[196:197]
	v_lshl_add_u64 v[198:199], v[76:77], 0, v[196:197]
	global_load_dwordx4 v[180:183], v[198:199], off
	global_load_dwordx4 v[184:187], v[198:199], off offset:1024
	global_load_dwordx4 v[188:191], v[198:199], off offset:2048
	global_load_dwordx4 v[192:195], v[198:199], off offset:3072
	v_pk_add_f32 v[104:105], v[92:93], v[70:71]
	v_mov_b32_e32 v107, v73
	v_pk_add_f32 v[104:105], v[94:95], v[104:105]
	v_mov_b32_e32 v106, v95
	v_pk_add_f32 v[104:105], v[72:73], v[104:105]
	v_mov_b32_e32 v95, v72
	v_add_f32_e32 v87, 0, v105
	v_add_f32_e32 v87, v104, v87
	v_pk_add_f32 v[104:105], v[88:89], v[66:67]
	v_mov_b32_e32 v108, v91
	v_pk_add_f32 v[104:105], v[90:91], v[104:105]
	v_mov_b32_e32 v109, v69
	v_pk_add_f32 v[104:105], v[68:69], v[104:105]
	v_mov_b32_e32 v91, v68
	v_add_f32_e32 v87, v105, v87
	v_add_f32_e32 v87, v104, v87
	ds_bpermute_b32 v103, v97, v87
	v_mov_b32_e32 v105, v71
	v_mov_b32_e32 v104, v93
	v_mov_b32_e32 v93, v70
	v_mov_b32_e32 v70, v89
	s_waitcnt lgkmcnt(0)
	v_add_f32_e32 v87, v87, v103
	ds_bpermute_b32 v103, v98, v87
	v_mov_b32_e32 v89, v66
	s_mov_b64 s[12:13], 0x1000
	s_waitcnt lgkmcnt(0)
	v_add_f32_e32 v87, v87, v103
	ds_bpermute_b32 v103, v99, v87
	s_waitcnt lgkmcnt(0)
	v_add_f32_e32 v87, v87, v103
	ds_bpermute_b32 v103, v100, v87
	s_waitcnt lgkmcnt(0)
	v_add_f32_e32 v71, v87, v103
	ds_bpermute_b32 v87, v101, v71
	v_add_u32_e32 v103, 1, v86
	v_cmp_lt_i32_e32 vcc, v103, v96
	v_cmp_ge_i32_e64 s[4:5], v103, v96
	s_or_b64 s[10:11], s[4:5], s[10:11]
	s_waitcnt lgkmcnt(0)
	v_add_f32_e32 v73, v71, v87
	ds_bpermute_b32 v87, v102, v73
	v_mov_b32_e32 v71, v67
	s_waitcnt lgkmcnt(0)
	v_add_f32_e32 v67, v73, v87
	v_mul_f32_e32 v72, 0x3a800000, v67
	v_pk_add_f32 v[112:113], v[104:105], v[72:73] op_sel_hi:[1,0] neg_lo:[0,1] neg_hi:[0,1]
	v_pk_add_f32 v[92:93], v[92:93], v[72:73] op_sel_hi:[1,0] neg_lo:[0,1] neg_hi:[0,1]
	v_pk_add_f32 v[116:117], v[70:71], v[72:73] op_sel_hi:[1,0] neg_lo:[0,1] neg_hi:[0,1]
	v_mov_b32_e32 v104, v113
	v_mov_b32_e32 v105, v93
	v_pk_add_f32 v[120:121], v[88:89], v[72:73] op_sel_hi:[1,0] neg_lo:[0,1] neg_hi:[0,1]
	v_pk_add_f32 v[114:115], v[106:107], v[72:73] op_sel_hi:[1,0] neg_lo:[0,1] neg_hi:[0,1]
	v_pk_add_f32 v[94:95], v[94:95], v[72:73] op_sel_hi:[1,0] neg_lo:[0,1] neg_hi:[0,1]
	v_mov_b32_e32 v70, v112
	v_mov_b32_e32 v71, v92
	v_pk_mul_f32 v[104:105], v[104:105], v[104:105]
	v_mov_b32_e32 v68, v121
	v_mov_b32_e32 v69, v117
	v_mov_b32_e32 v106, v114
	v_mov_b32_e32 v107, v94
	v_pk_fma_f32 v[70:71], v[70:71], v[70:71], v[104:105]
	v_pk_add_f32 v[118:119], v[108:109], v[72:73] op_sel_hi:[1,0] neg_lo:[0,1] neg_hi:[0,1]
	v_pk_add_f32 v[122:123], v[90:91], v[72:73] op_sel_hi:[1,0] neg_lo:[0,1] neg_hi:[0,1]
	v_mov_b32_e32 v66, v120
	v_mov_b32_e32 v67, v116
	v_pk_mul_f32 v[68:69], v[68:69], v[68:69]
	v_mov_b32_e32 v110, v115
	v_mov_b32_e32 v111, v95
	v_pk_fma_f32 v[70:71], v[106:107], v[106:107], v[70:71]
	v_pk_fma_f32 v[66:67], v[66:67], v[66:67], v[68:69]
	v_mov_b32_e32 v68, v122
	v_mov_b32_e32 v69, v118
	v_pk_fma_f32 v[70:71], v[110:111], v[110:111], v[70:71]
	v_mov_b32_e32 v72, v123
	v_mov_b32_e32 v73, v119
	v_pk_fma_f32 v[66:67], v[68:69], v[68:69], v[66:67]
	v_add_f32_e32 v68, v70, v71
	v_pk_fma_f32 v[66:67], v[72:73], v[72:73], v[66:67]
	s_nop 0
	v_add_f32_e32 v67, v67, v68
	v_add_f32_e32 v66, v66, v67
	ds_bpermute_b32 v67, v97, v66
	s_waitcnt lgkmcnt(0)
	v_add_f32_e32 v66, v66, v67
	ds_bpermute_b32 v67, v98, v66
	s_waitcnt lgkmcnt(0)
	v_add_f32_e32 v68, v66, v67
	ds_bpermute_b32 v69, v99, v68
	s_waitcnt lgkmcnt(0)
	v_add_f32_e32 v88, v68, v69
	ds_bpermute_b32 v89, v100, v88
	s_waitcnt lgkmcnt(0)
	v_add_f32_e32 v88, v88, v89
	ds_bpermute_b32 v89, v101, v88
	s_waitcnt lgkmcnt(0)
	v_add_f32_e32 v86, v88, v89
	ds_bpermute_b32 v87, v102, v86
	s_waitcnt lgkmcnt(0)
; DI u32x2 pk4(float a, float b, float c, float d) { u32x2 r; r.x = pk2(a, b); r.y = pk2(c, d); return r; }
; DI void ln_mod_phase(KParamPtr P, int wv, const float* src, float* xdst, const float* lng, const float* lnb, const float* sh, const float* sc, bool do_ln, bool write_hb) {
;     ...
;     const int bb = row >> 13;
;     if (bb != curb && write_hb) {
;       curb = bb;
; #pragma unroll
;       for (int i = 0; i < 4; ++i) { int c = lane * 4 + 256 * i; sh4[i] = *(const float4*)(sh + bb * 6144 + c); sc4[i] = *(const float4*)(sc + bb * 6144 + c); }
;     }
;     ...
;       const float rstd = rsqrtf(wave_sum(q, lane) * (1.f / 1024.f) + 1e-5f);
; #pragma unroll
;       for (int i = 0; i < 4; ++i) {
;         v[i].x = v[i].x * rstd * g4[i].x + b4[i].x; v[i].y = v[i].y * rstd * g4[i].y + b4[i].y; v[i].z = v[i].z * rstd * g4[i].z + b4[i].z; v[i].w = v[i].w * rstd * g4[i].w + b4[i].w;
;         *(float4*)(xdst + (size_t)row * DM + lane * 4 + 256 * i) = v[i];
;       }
;     }
;     if (write_hb) {
; #pragma unroll
;       for (int i = 0; i < 4; ++i) {
;         *(u32x2*)(hb + (size_t)row * DM + lane * 4 + 256 * i) = pk4(v[i].x * (one + sc4[i].x) + sh4[i].x, v[i].y * (one + sc4[i].y) + sh4[i].y, v[i].z * (one + sc4[i].z) + sh4[i].z, v[i].w * (one + sc4[i].w) + sh4[i].w);
;       }
;     }
;   }
	v_add_f32_e32 v86, v86, v87
	v_fmamk_f32 v86, v86, 0x3a800000, v215
	v_mul_f32_e32 v87, 0x4b800000, v86
	v_cmp_gt_f32_e32 vcc, s68, v86
	s_nop 1
	v_cndmask_b32_e32 v86, v86, v87, vcc
	v_rsq_f32_e32 v86, v86
	s_nop 0
	v_mul_f32_e32 v87, 0x45800000, v86
	v_cndmask_b32_e32 v124, v86, v87, vcc
	v_pk_mul_f32 v[90:91], v[92:93], v[124:125] op_sel_hi:[1,0]
	v_pk_mul_f32 v[92:93], v[94:95], v[124:125] op_sel_hi:[1,0]
	v_pk_mul_f32 v[94:95], v[116:117], v[124:125] op_sel_hi:[1,0]
	v_pk_mul_f32 v[86:87], v[112:113], v[124:125] op_sel_hi:[1,0]
	v_pk_fma_f32 v[112:113], v[18:19], v[94:95], v[26:27]
	v_pk_mul_f32 v[94:95], v[118:119], v[124:125] op_sel_hi:[1,0]
	v_pk_mul_f32 v[88:89], v[114:115], v[124:125] op_sel_hi:[1,0]
	v_pk_fma_f32 v[114:115], v[20:21], v[94:95], v[28:29]
	v_pk_mul_f32 v[94:95], v[120:121], v[124:125] op_sel_hi:[1,0]
	v_pk_fma_f32 v[86:87], v[2:3], v[86:87], v[10:11]
	v_pk_fma_f32 v[116:117], v[22:23], v[94:95], v[30:31]
	v_pk_mul_f32 v[94:95], v[122:123], v[124:125] op_sel_hi:[1,0]
	v_pk_fma_f32 v[88:89], v[4:5], v[88:89], v[12:13]
	v_pk_fma_f32 v[118:119], v[24:25], v[94:95], v[32:33]
	s_waitcnt vmcnt(4)
	v_pk_add_f32 v[94:95], v[74:75], v[42:43]
	global_store_dwordx4 v[82:83], v[86:89], off offset:-2048
	v_pk_fma_f32 v[90:91], v[6:7], v[90:91], v[14:15]
	v_pk_fma_f32 v[92:93], v[8:9], v[92:93], v[16:17]
	v_pk_fma_f32 v[86:87], v[94:95], v[86:87], v[34:35]
	v_pk_add_f32 v[94:95], v[74:75], v[44:45]
	v_cvt_pk_bf16_f32 v86, v86, v87
	v_pk_fma_f32 v[88:89], v[94:95], v[88:89], v[36:37]
	global_store_dwordx4 v[82:83], v[90:93], off offset:-1024
	v_cvt_pk_bf16_f32 v87, v88, v89
	global_store_dwordx4 v[82:83], v[112:115], off
	global_store_dwordx4 v[82:83], v[116:119], off offset:1024
	global_store_dwordx2 v[84:85], v[86:87], off
	v_pk_add_f32 v[86:87], v[74:75], v[50:51]
	v_pk_add_f32 v[88:89], v[74:75], v[52:53]
	v_pk_fma_f32 v[86:87], v[86:87], v[90:91], v[38:39]
	v_pk_fma_f32 v[88:89], v[88:89], v[92:93], v[40:41]
	v_cvt_pk_bf16_f32 v86, v86, v87
	v_cvt_pk_bf16_f32 v87, v88, v89
	global_store_dwordx2 v[84:85], v[86:87], off offset:512
	v_pk_add_f32 v[86:87], v[74:75], v[58:59]
	v_pk_add_f32 v[88:89], v[74:75], v[60:61]
	v_pk_fma_f32 v[86:87], v[86:87], v[112:113], v[46:47]
	v_pk_fma_f32 v[88:89], v[88:89], v[114:115], v[48:49]
	v_cvt_pk_bf16_f32 v86, v86, v87
	v_cvt_pk_bf16_f32 v87, v88, v89
	global_store_dwordx2 v[84:85], v[86:87], off offset:1024
	v_pk_add_f32 v[86:87], v[74:75], v[62:63]
	v_pk_add_f32 v[88:89], v[74:75], v[64:65]
	v_pk_fma_f32 v[86:87], v[86:87], v[116:117], v[54:55]
	v_pk_fma_f32 v[88:89], v[88:89], v[118:119], v[56:57]
	v_cvt_pk_bf16_f32 v86, v86, v87
	v_cvt_pk_bf16_f32 v87, v88, v89
	v_lshl_add_u64 v[82:83], v[82:83], 0, s[12:13]
	s_mov_b64 s[12:13], 0x800
	global_store_dwordx2 v[84:85], v[86:87], off offset:1536
	v_lshl_add_u64 v[84:85], v[84:85], 0, s[12:13]
	v_mov_b32_e32 v86, v103
	s_waitcnt vmcnt(8)
	v_mov_b32_e32 v93, v180
	v_mov_b32_e32 v71, v181
	v_mov_b32_e32 v95, v182
	v_mov_b32_e32 v73, v183
	v_mov_b32_e32 v92, v184
	v_mov_b32_e32 v70, v185
	v_mov_b32_e32 v94, v186
	v_mov_b32_e32 v72, v187
	v_mov_b32_e32 v89, v188
	v_mov_b32_e32 v67, v189
	v_mov_b32_e32 v91, v190
	v_mov_b32_e32 v69, v191
	v_mov_b32_e32 v88, v192
	v_mov_b32_e32 v66, v193
	v_mov_b32_e32 v90, v194
	v_mov_b32_e32 v68, v195
	s_andn2_b64 exec, exec, s[10:11]
	s_cbranch_execz .LBB0_1258
.LBB0_1256:
	v_ashrrev_i32_e32 v87, 13, v86
	v_cmp_ne_u32_e32 vcc, v87, v0
	s_and_saveexec_b64 s[4:5], vcc
	s_cbranch_execz .LBB0_1255
	v_mul_i32_i24_e32 v34, 0x1800, v87
	v_ashrrev_i32_e32 v35, 31, v34
	v_lshlrev_b64 v[34:35], 2, v[34:35]
	v_lshl_add_u64 v[54:55], v[78:79], 0, v[34:35]
	v_lshl_add_u64 v[62:63], v[80:81], 0, v[34:35]
	flat_load_dwordx4 v[34:37], v[54:55]
	flat_load_dwordx4 v[38:41], v[54:55] offset:1024
	flat_load_dwordx4 v[42:45], v[62:63]
	flat_load_dwordx4 v[50:53], v[62:63] offset:1024
	flat_load_dwordx4 v[46:49], v[54:55] offset:2048
	s_nop 0
	flat_load_dwordx4 v[54:57], v[54:55] offset:3072
	s_nop 0
	flat_load_dwordx4 v[58:61], v[62:63] offset:2048
	s_nop 0
	flat_load_dwordx4 v[62:65], v[62:63] offset:3072
	v_mov_b32_e32 v0, v87
	s_waitcnt vmcnt(0) lgkmcnt(0)
	s_branch .LBB0_1255
